# deferred weight transposes split by deadline: part of w_up on P10 idle WGs, w_down in P14 last-round slack, rest in P3 tail
# speedup vs baseline: 1.0053x; 1.0053x over previous
.LBB0_693:
	s_cmp_lt_u32 s2, 8
	s_barrier
	s_cbranch_scc1 .LBB0_950
	s_mov_b64 exec, -1
	v_readlane_b32 s0, v254, 0
	v_readlane_b32 s1, v254, 1
	s_nop 4
	s_load_dwordx2 s[56:57], s[0:1], 0xa8
	s_load_dwordx2 s[58:59], s[0:1], 0xc0
	s_load_dwordx2 s[60:61], s[0:1], 0x88
	s_load_dwordx2 s[62:63], s[0:1], 0x78
	s_load_dwordx2 s[64:65], s[0:1], 0x80
	s_load_dwordx2 s[66:67], s[0:1], 0x90
	s_load_dwordx2 s[68:69], s[0:1], 0xa0
	s_load_dwordx2 s[70:71], s[0:1], 0x48
	s_load_dwordx2 s[72:73], s[0:1], 0xd8
	s_load_dword s3, s[0:1], 0xe8
	v_readfirstlane_b32 s4, v0
	v_and_b32_e32 v7, 63, v0
	s_lshr_b32 s4, s4, 6
	v_lshrrev_b32_e32 v1, 3, v7
	v_and_b32_e32 v2, 7, v7
	s_lshl_b32 s5, s4, 14
	v_lshlrev_b32_e32 v5, 5, v2
	s_movk_i32 s14, 0x420
	v_mul_u32_u24_e32 v4, s14, v2
	v_lshlrev_b32_e32 v2, 4, v2
	s_movk_i32 s14, 0x84
	v_mad_u32_u24 v3, v1, s14, v2
	v_lshl_add_u32 v4, v1, 2, v4
	v_add_u32_e32 v3, s5, v3
	v_add_u32_e32 v4, s5, v4
	v_mov_b32_e32 v207, v3
	v_add_u32_e32 v208, 1056, v3
	v_add_u32_e32 v209, 2112, v3
	v_add_u32_e32 v210, 3168, v3
	v_add_u32_e32 v211, 4224, v3
	v_add_u32_e32 v212, 5280, v3
	v_add_u32_e32 v213, 6336, v3
	v_add_u32_e32 v214, 7392, v3
	s_waitcnt lgkmcnt(0)
	s_sub_u32 s5, s2, 8
	s_lshl_b32 s5, s5, 3
	s_add_u32 s20, s5, s4
	s_sub_u32 s21, s3, 8
	s_lshl_b32 s21, s21, 3
	s_cmp_ge_u32 s20, 0x3460
	s_cbranch_scc1 .Lrc_p3call
	s_mov_b32 s42, 0
	s_mov_b32 s43, 0
	s_mov_b32 s26, s20
	s_cmp_lt_u32 s26, 0x400
	s_cbranch_scc1 .Ltrp3_i1_s0
	s_sub_u32 s26, s26, 0x400
	s_cmp_lt_u32 s26, 0x400
	s_cbranch_scc1 .Ltrp3_i1_s1
	s_sub_u32 s26, s26, 0x400
	s_cmp_lt_u32 s26, 0x800
	s_cbranch_scc1 .Ltrp3_i1_s2
	s_sub_u32 s26, s26, 0x800
	s_cmp_lt_u32 s26, 0x200
	s_cbranch_scc1 .Ltrp3_i1_s3
	s_sub_u32 s26, s26, 0x200
	s_cmp_lt_u32 s26, 0x200
	s_cbranch_scc1 .Ltrp3_i1_s4
	s_sub_u32 s26, s26, 0x200
	s_cmp_lt_u32 s26, 0x2c00
	s_cbranch_scc1 .Ltrp3_i1_s5
	s_sub_u32 s26, s26, 0x2c00
	s_branch .Ltrp3_i1_s6

.Ltrp3_i1_s1:
	s_mov_b64 s[22:23], s[64:65]
	s_mov_b32 s24, 0x2000
	s_lshr_b32 s25, s26, 6
	s_and_b32 s27, s26, 63
	s_mov_b32 s28, 0x2200800
	s_mov_b32 s29, 0x1000
	s_mov_b32 s30, 0
	s_mov_b32 s31, 0
	s_branch .Ltrp3_i1_c
.Ltrp3_i1_s2:
	s_mov_b64 s[22:23], s[60:61]
	s_mov_b32 s24, 0x2000
	s_lshr_b32 s25, s26, 6
	s_and_b32 s27, s26, 63
	s_mov_b32 s28, 0x2a00000
	s_mov_b32 s29, 0x1000
	s_mov_b32 s30, 0
	s_mov_b32 s31, 0
	s_branch .Ltrp3_i1_c
.Ltrp3_i1_s3:
	s_mov_b64 s[22:23], s[66:67]
	s_mov_b32 s24, 0x800
	s_lshr_b32 s25, s26, 4
	s_and_b32 s27, s26, 15
	s_mov_b32 s28, 0x3200000
	s_mov_b32 s29, 0x1000
	s_mov_b32 s30, 0x2000
	s_mov_b32 s31, 1
	s_branch .Ltrp3_i1_c
.Ltrp3_i1_s4:
	s_mov_b64 s[22:23], s[68:69]
	s_mov_b32 s24, 0x2000
	s_lshr_b32 s25, s26, 6
	s_and_b32 s27, s26, 63
	s_mov_b32 s28, 0x3800000
	s_mov_b32 s29, 0x400
	s_mov_b32 s30, 0
	s_mov_b32 s31, 0
	s_branch .Ltrp3_i1_c

.Ltrp3_i1_c:
	s_lshl_b32 s4, s24, 6
	s_mul_i32 s4, s25, s4
	s_lshl_b32 s5, s27, 7
	s_add_u32 s4, s4, s5
	s_add_u32 s10, s22, s4
	s_addc_u32 s11, s23, 0
	v_mad_u32_u24 v6, v1, s24, v2
	s_lshl_b32 s4, s29, 5
	s_mul_i32 s4, s27, s4
	s_lshl_b32 s5, s25, 7
	s_add_u32 s4, s4, s5
	s_add_u32 s4, s4, s28
	s_add_u32 s74, s72, s4
	s_addc_u32 s75, s73, 0
	s_mov_b32 s76, s29
	s_mov_b32 s77, s31
	s_lshl_b32 s4, s25, 8
	s_add_u32 s4, s4, s30
	s_add_u32 s12, s70, s4
	s_addc_u32 s13, s71, 0
	s_lshl_b32 s14, s24, 3
	global_load_dwordx4 v[44:47], v6, s[10:11]
	s_add_u32 s10, s10, s14
	s_addc_u32 s11, s11, 0
	global_load_dwordx4 v[48:51], v6, s[10:11]
	s_add_u32 s10, s10, s14
	s_addc_u32 s11, s11, 0
	global_load_dwordx4 v[52:55], v6, s[10:11]
	s_add_u32 s10, s10, s14
	s_addc_u32 s11, s11, 0
	global_load_dwordx4 v[56:59], v6, s[10:11]
	s_add_u32 s10, s10, s14
	s_addc_u32 s11, s11, 0
	global_load_dwordx4 v[60:63], v6, s[10:11]
	s_add_u32 s10, s10, s14
	s_addc_u32 s11, s11, 0
	global_load_dwordx4 v[64:67], v6, s[10:11]
	s_add_u32 s10, s10, s14
	s_addc_u32 s11, s11, 0
	global_load_dwordx4 v[68:71], v6, s[10:11]
	s_add_u32 s10, s10, s14
	s_addc_u32 s11, s11, 0
	global_load_dwordx4 v[72:75], v6, s[10:11]
	global_load_dwordx4 v[76:79], v5, s[12:13]
	global_load_dwordx4 v[80:83], v5, s[12:13] offset:16
	s_add_u32 s20, s20, s21
	s_add_u32 s42, s42, 1
	s_cmp_ge_u32 s20, 0x3460
	s_cbranch_scc1 .Ltrp3_st0
	s_mov_b32 s26, s20
	s_cmp_lt_u32 s26, 0x400
	s_cbranch_scc1 .Ltrp3_i2_s0
	s_sub_u32 s26, s26, 0x400
	s_cmp_lt_u32 s26, 0x400
	s_cbranch_scc1 .Ltrp3_i2_s1
	s_sub_u32 s26, s26, 0x400
	s_cmp_lt_u32 s26, 0x800
	s_cbranch_scc1 .Ltrp3_i2_s2
	s_sub_u32 s26, s26, 0x800
	s_cmp_lt_u32 s26, 0x200
	s_cbranch_scc1 .Ltrp3_i2_s3
	s_sub_u32 s26, s26, 0x200
	s_cmp_lt_u32 s26, 0x200
	s_cbranch_scc1 .Ltrp3_i2_s4
	s_sub_u32 s26, s26, 0x200
	s_cmp_lt_u32 s26, 0x2c00
	s_cbranch_scc1 .Ltrp3_i2_s5
	s_sub_u32 s26, s26, 0x2c00
	s_branch .Ltrp3_i2_s6

.Ltrp3_i2_s1:
	s_mov_b64 s[22:23], s[64:65]
	s_mov_b32 s24, 0x2000
	s_lshr_b32 s25, s26, 6
	s_and_b32 s27, s26, 63
	s_mov_b32 s28, 0x2200800
	s_mov_b32 s29, 0x1000
	s_mov_b32 s30, 0
	s_mov_b32 s31, 0
	s_branch .Ltrp3_i2_c
.Ltrp3_i2_s2:
	s_mov_b64 s[22:23], s[60:61]
	s_mov_b32 s24, 0x2000
	s_lshr_b32 s25, s26, 6
	s_and_b32 s27, s26, 63
	s_mov_b32 s28, 0x2a00000
	s_mov_b32 s29, 0x1000
	s_mov_b32 s30, 0
	s_mov_b32 s31, 0
	s_branch .Ltrp3_i2_c
.Ltrp3_i2_s3:
	s_mov_b64 s[22:23], s[66:67]
	s_mov_b32 s24, 0x800
	s_lshr_b32 s25, s26, 4
	s_and_b32 s27, s26, 15
	s_mov_b32 s28, 0x3200000
	s_mov_b32 s29, 0x1000
	s_mov_b32 s30, 0x2000
	s_mov_b32 s31, 1
	s_branch .Ltrp3_i2_c

.Ltrp3_i2_c:
	s_lshl_b32 s4, s24, 6
	s_mul_i32 s4, s25, s4
	s_lshl_b32 s5, s27, 7
	s_add_u32 s4, s4, s5
	s_add_u32 s10, s22, s4
	s_addc_u32 s11, s23, 0
	v_mad_u32_u24 v6, v1, s24, v2
	s_lshl_b32 s4, s29, 5
	s_mul_i32 s4, s27, s4
	s_lshl_b32 s5, s25, 7
	s_add_u32 s4, s4, s5
	s_add_u32 s4, s4, s28
	s_add_u32 s78, s72, s4
	s_addc_u32 s79, s73, 0
	s_mov_b32 s80, s29
	s_mov_b32 s81, s31
	s_lshl_b32 s4, s25, 8
	s_add_u32 s4, s4, s30
	s_add_u32 s12, s70, s4
	s_addc_u32 s13, s71, 0
	s_lshl_b32 s14, s24, 3
	global_load_dwordx4 v[84:87], v6, s[10:11]
	s_add_u32 s10, s10, s14
	s_addc_u32 s11, s11, 0
	global_load_dwordx4 v[88:91], v6, s[10:11]
	s_add_u32 s10, s10, s14
	s_addc_u32 s11, s11, 0
	global_load_dwordx4 v[92:95], v6, s[10:11]
	s_add_u32 s10, s10, s14
	s_addc_u32 s11, s11, 0
	global_load_dwordx4 v[96:99], v6, s[10:11]
	s_add_u32 s10, s10, s14
	s_addc_u32 s11, s11, 0
	global_load_dwordx4 v[100:103], v6, s[10:11]
	s_add_u32 s10, s10, s14
	s_addc_u32 s11, s11, 0
	global_load_dwordx4 v[104:107], v6, s[10:11]
	s_add_u32 s10, s10, s14
	s_addc_u32 s11, s11, 0
	global_load_dwordx4 v[108:111], v6, s[10:11]
	s_add_u32 s10, s10, s14
	s_addc_u32 s11, s11, 0
	global_load_dwordx4 v[112:115], v6, s[10:11]
	global_load_dwordx4 v[116:119], v5, s[12:13]
	global_load_dwordx4 v[120:123], v5, s[12:13] offset:16
	s_add_u32 s20, s20, s21
	s_add_u32 s42, s42, 1
	s_cmp_ge_u32 s20, 0x3460
	s_cbranch_scc1 .Ltrp3_st0
	s_mov_b32 s26, s20
	s_cmp_lt_u32 s26, 0x400
	s_cbranch_scc1 .Ltrp3_i3_s0
	s_sub_u32 s26, s26, 0x400
	s_cmp_lt_u32 s26, 0x400
	s_cbranch_scc1 .Ltrp3_i3_s1
	s_sub_u32 s26, s26, 0x400
	s_cmp_lt_u32 s26, 0x800
	s_cbranch_scc1 .Ltrp3_i3_s2
	s_sub_u32 s26, s26, 0x800
	s_cmp_lt_u32 s26, 0x200
	s_cbranch_scc1 .Ltrp3_i3_s3
	s_sub_u32 s26, s26, 0x200
	s_cmp_lt_u32 s26, 0x200
	s_cbranch_scc1 .Ltrp3_i3_s4
	s_sub_u32 s26, s26, 0x200
	s_cmp_lt_u32 s26, 0x2c00
	s_cbranch_scc1 .Ltrp3_i3_s5
	s_sub_u32 s26, s26, 0x2c00
	s_branch .Ltrp3_i3_s6

.Ltrp3_i3_s1:
	s_mov_b64 s[22:23], s[64:65]
	s_mov_b32 s24, 0x2000
	s_lshr_b32 s25, s26, 6
	s_and_b32 s27, s26, 63
	s_mov_b32 s28, 0x2200800
	s_mov_b32 s29, 0x1000
	s_mov_b32 s30, 0
	s_mov_b32 s31, 0
	s_branch .Ltrp3_i3_c
.Ltrp3_i3_s2:
	s_mov_b64 s[22:23], s[60:61]
	s_mov_b32 s24, 0x2000
	s_lshr_b32 s25, s26, 6
	s_and_b32 s27, s26, 63
	s_mov_b32 s28, 0x2a00000
	s_mov_b32 s29, 0x1000
	s_mov_b32 s30, 0
	s_mov_b32 s31, 0
	s_branch .Ltrp3_i3_c
.Ltrp3_i3_s3:
	s_mov_b64 s[22:23], s[66:67]
	s_mov_b32 s24, 0x800
	s_lshr_b32 s25, s26, 4
	s_and_b32 s27, s26, 15
	s_mov_b32 s28, 0x3200000
	s_mov_b32 s29, 0x1000
	s_mov_b32 s30, 0x2000
	s_mov_b32 s31, 1
	s_branch .Ltrp3_i3_c

.Ltrp3_i3_c:
	s_lshl_b32 s4, s24, 6
	s_mul_i32 s4, s25, s4
	s_lshl_b32 s5, s27, 7
	s_add_u32 s4, s4, s5
	s_add_u32 s10, s22, s4
	s_addc_u32 s11, s23, 0
	v_mad_u32_u24 v6, v1, s24, v2
	s_lshl_b32 s4, s29, 5
	s_mul_i32 s4, s27, s4
	s_lshl_b32 s5, s25, 7
	s_add_u32 s4, s4, s5
	s_add_u32 s4, s4, s28
	s_add_u32 s82, s72, s4
	s_addc_u32 s83, s73, 0
	s_mov_b32 s84, s29
	s_mov_b32 s85, s31
	s_lshl_b32 s4, s25, 8
	s_add_u32 s4, s4, s30
	s_add_u32 s12, s70, s4
	s_addc_u32 s13, s71, 0
	s_lshl_b32 s14, s24, 3
	global_load_dwordx4 v[124:127], v6, s[10:11]
	s_add_u32 s10, s10, s14
	s_addc_u32 s11, s11, 0
	global_load_dwordx4 v[128:131], v6, s[10:11]
	s_add_u32 s10, s10, s14
	s_addc_u32 s11, s11, 0
	global_load_dwordx4 v[132:135], v6, s[10:11]
	s_add_u32 s10, s10, s14
	s_addc_u32 s11, s11, 0
	global_load_dwordx4 v[136:139], v6, s[10:11]
	s_add_u32 s10, s10, s14
	s_addc_u32 s11, s11, 0
	global_load_dwordx4 v[140:143], v6, s[10:11]
	s_add_u32 s10, s10, s14
	s_addc_u32 s11, s11, 0
	global_load_dwordx4 v[144:147], v6, s[10:11]
	s_add_u32 s10, s10, s14
	s_addc_u32 s11, s11, 0
	global_load_dwordx4 v[148:151], v6, s[10:11]
	s_add_u32 s10, s10, s14
	s_addc_u32 s11, s11, 0
	global_load_dwordx4 v[152:155], v6, s[10:11]
	global_load_dwordx4 v[156:159], v5, s[12:13]
	global_load_dwordx4 v[160:163], v5, s[12:13] offset:16
	s_add_u32 s20, s20, s21
	s_add_u32 s42, s42, 1
	s_cmp_ge_u32 s20, 0x3460
	s_cbranch_scc1 .Ltrp3_st0
	s_mov_b32 s26, s20
	s_cmp_lt_u32 s26, 0x400
	s_cbranch_scc1 .Ltrp3_i4_s0
	s_sub_u32 s26, s26, 0x400
	s_cmp_lt_u32 s26, 0x400
	s_cbranch_scc1 .Ltrp3_i4_s1
	s_sub_u32 s26, s26, 0x400
	s_cmp_lt_u32 s26, 0x800
	s_cbranch_scc1 .Ltrp3_i4_s2
	s_sub_u32 s26, s26, 0x800
	s_cmp_lt_u32 s26, 0x200
	s_cbranch_scc1 .Ltrp3_i4_s3
	s_sub_u32 s26, s26, 0x200
	s_cmp_lt_u32 s26, 0x200
	s_cbranch_scc1 .Ltrp3_i4_s4
	s_sub_u32 s26, s26, 0x200
	s_cmp_lt_u32 s26, 0x2c00
	s_cbranch_scc1 .Ltrp3_i4_s5
	s_sub_u32 s26, s26, 0x2c00
	s_branch .Ltrp3_i4_s6

.Ltrp3_i4_s1:
	s_mov_b64 s[22:23], s[64:65]
	s_mov_b32 s24, 0x2000
	s_lshr_b32 s25, s26, 6
	s_and_b32 s27, s26, 63
	s_mov_b32 s28, 0x2200800
	s_mov_b32 s29, 0x1000
	s_mov_b32 s30, 0
	s_mov_b32 s31, 0
	s_branch .Ltrp3_i4_c
.Ltrp3_i4_s2:
	s_mov_b64 s[22:23], s[60:61]
	s_mov_b32 s24, 0x2000
	s_lshr_b32 s25, s26, 6
	s_and_b32 s27, s26, 63
	s_mov_b32 s28, 0x2a00000
	s_mov_b32 s29, 0x1000
	s_mov_b32 s30, 0
	s_mov_b32 s31, 0
	s_branch .Ltrp3_i4_c
.Ltrp3_i4_s3:
	s_mov_b64 s[22:23], s[66:67]
	s_mov_b32 s24, 0x800
	s_lshr_b32 s25, s26, 4
	s_and_b32 s27, s26, 15
	s_mov_b32 s28, 0x3200000
	s_mov_b32 s29, 0x1000
	s_mov_b32 s30, 0x2000
	s_mov_b32 s31, 1
	s_branch .Ltrp3_i4_c

.Ltrp3_i4_s6:
	s_mov_b64 s[22:23], s[58:59]
	s_mov_b32 s24, 0x2000
	s_lshr_b32 s25, s26, 6
	s_and_b32 s27, s26, 63
	s_mov_b32 s28, 0x6600000
	s_mov_b32 s29, 0x2c00
	s_mov_b32 s30, 0
	s_mov_b32 s31, 0
.Ltrp3_i4_c:
	s_lshl_b32 s4, s24, 6
	s_mul_i32 s4, s25, s4
	s_lshl_b32 s5, s27, 7
	s_add_u32 s4, s4, s5
	s_add_u32 s10, s22, s4
	s_addc_u32 s11, s23, 0
	v_mad_u32_u24 v6, v1, s24, v2
	s_lshl_b32 s4, s29, 5
	s_mul_i32 s4, s27, s4
	s_lshl_b32 s5, s25, 7
	s_add_u32 s4, s4, s5
	s_add_u32 s4, s4, s28
	s_add_u32 s86, s72, s4
	s_addc_u32 s87, s73, 0
	s_mov_b32 s88, s29
	s_mov_b32 s90, s31
	s_lshl_b32 s4, s25, 8
	s_add_u32 s4, s4, s30
	s_add_u32 s12, s70, s4
	s_addc_u32 s13, s71, 0
	s_lshl_b32 s14, s24, 3
	global_load_dwordx4 v[164:167], v6, s[10:11]
	s_add_u32 s10, s10, s14
	s_addc_u32 s11, s11, 0
	global_load_dwordx4 v[168:171], v6, s[10:11]
	s_add_u32 s10, s10, s14
	s_addc_u32 s11, s11, 0
	global_load_dwordx4 v[172:175], v6, s[10:11]
	s_add_u32 s10, s10, s14
	s_addc_u32 s11, s11, 0
	global_load_dwordx4 v[176:179], v6, s[10:11]
	s_add_u32 s10, s10, s14
	s_addc_u32 s11, s11, 0
	global_load_dwordx4 v[180:183], v6, s[10:11]
	s_add_u32 s10, s10, s14
	s_addc_u32 s11, s11, 0
	global_load_dwordx4 v[184:187], v6, s[10:11]
	s_add_u32 s10, s10, s14
	s_addc_u32 s11, s11, 0
	global_load_dwordx4 v[188:191], v6, s[10:11]
	s_add_u32 s10, s10, s14
	s_addc_u32 s11, s11, 0
	global_load_dwordx4 v[192:195], v6, s[10:11]
	global_load_dwordx4 v[196:199], v5, s[12:13]
	global_load_dwordx4 v[200:203], v5, s[12:13] offset:16
	s_add_u32 s20, s20, s21
	s_add_u32 s42, s42, 1

.Ltrp3_p5_ng:
	v_cvt_pk_bf16_f32 v12, v12, v13
	v_cvt_pk_bf16_f32 v13, v14, v15
	v_cvt_pk_bf16_f32 v14, v16, v17
	v_cvt_pk_bf16_f32 v15, v18, v19
	v_cvt_pk_bf16_f32 v20, v20, v21
	v_cvt_pk_bf16_f32 v21, v22, v23
	v_cvt_pk_bf16_f32 v22, v24, v25
	v_cvt_pk_bf16_f32 v23, v26, v27
	v_cvt_pk_bf16_f32 v28, v28, v29
	v_cvt_pk_bf16_f32 v29, v30, v31
	v_cvt_pk_bf16_f32 v30, v32, v33
	v_cvt_pk_bf16_f32 v31, v34, v35
	v_cvt_pk_bf16_f32 v36, v36, v37
	v_cvt_pk_bf16_f32 v37, v38, v39
	v_cvt_pk_bf16_f32 v38, v40, v41
	v_cvt_pk_bf16_f32 v39, v42, v43
	global_store_dwordx4 v8, v[12:15], s[74:75]
	global_store_dwordx4 v9, v[20:23], s[74:75]
	global_store_dwordx4 v10, v[28:31], s[74:75]
	global_store_dwordx4 v11, v[36:39], s[74:75]
	s_sub_u32 s42, s42, 1
	s_add_u32 s43, s43, 1
	s_cmp_ge_u32 s20, 0x3460
	s_cbranch_scc1 .Ltrp3_ni_0
	s_mov_b32 s26, s20
	s_cmp_lt_u32 s26, 0x400
	s_cbranch_scc1 .Ltrp3_i6_s0
	s_sub_u32 s26, s26, 0x400
	s_cmp_lt_u32 s26, 0x400
	s_cbranch_scc1 .Ltrp3_i6_s1
	s_sub_u32 s26, s26, 0x400
	s_cmp_lt_u32 s26, 0x800
	s_cbranch_scc1 .Ltrp3_i6_s2
	s_sub_u32 s26, s26, 0x800
	s_cmp_lt_u32 s26, 0x200
	s_cbranch_scc1 .Ltrp3_i6_s3
	s_sub_u32 s26, s26, 0x200
	s_cmp_lt_u32 s26, 0x200
	s_cbranch_scc1 .Ltrp3_i6_s4
	s_sub_u32 s26, s26, 0x200
	s_cmp_lt_u32 s26, 0x2c00
	s_cbranch_scc1 .Ltrp3_i6_s5
	s_sub_u32 s26, s26, 0x2c00
	s_branch .Ltrp3_i6_s6

.Ltrp3_i6_s1:
	s_mov_b64 s[22:23], s[64:65]
	s_mov_b32 s24, 0x2000
	s_lshr_b32 s25, s26, 6
	s_and_b32 s27, s26, 63
	s_mov_b32 s28, 0x2200800
	s_mov_b32 s29, 0x1000
	s_mov_b32 s30, 0
	s_mov_b32 s31, 0
	s_branch .Ltrp3_i6_c
.Ltrp3_i6_s2:
	s_mov_b64 s[22:23], s[60:61]
	s_mov_b32 s24, 0x2000
	s_lshr_b32 s25, s26, 6
	s_and_b32 s27, s26, 63
	s_mov_b32 s28, 0x2a00000
	s_mov_b32 s29, 0x1000
	s_mov_b32 s30, 0
	s_mov_b32 s31, 0
	s_branch .Ltrp3_i6_c
.Ltrp3_i6_s3:
	s_mov_b64 s[22:23], s[66:67]
	s_mov_b32 s24, 0x800
	s_lshr_b32 s25, s26, 4
	s_and_b32 s27, s26, 15
	s_mov_b32 s28, 0x3200000
	s_mov_b32 s29, 0x1000
	s_mov_b32 s30, 0x2000
	s_mov_b32 s31, 1
	s_branch .Ltrp3_i6_c

.Ltrp3_i6_s6:
	s_mov_b64 s[22:23], s[58:59]
	s_mov_b32 s24, 0x2000
	s_lshr_b32 s25, s26, 6
	s_and_b32 s27, s26, 63
	s_mov_b32 s28, 0x6600000
	s_mov_b32 s29, 0x2c00
	s_mov_b32 s30, 0
	s_mov_b32 s31, 0
.Ltrp3_i6_c:
	s_lshl_b32 s4, s24, 6
	s_mul_i32 s4, s25, s4
	s_lshl_b32 s5, s27, 7
	s_add_u32 s4, s4, s5
	s_add_u32 s10, s22, s4
	s_addc_u32 s11, s23, 0
	v_mad_u32_u24 v6, v1, s24, v2
	s_lshl_b32 s4, s29, 5
	s_mul_i32 s4, s27, s4
	s_lshl_b32 s5, s25, 7
	s_add_u32 s4, s4, s5
	s_add_u32 s4, s4, s28
	s_add_u32 s74, s72, s4
	s_addc_u32 s75, s73, 0
	s_mov_b32 s76, s29
	s_mov_b32 s77, s31
	s_lshl_b32 s4, s25, 8
	s_add_u32 s4, s4, s30
	s_add_u32 s12, s70, s4
	s_addc_u32 s13, s71, 0
	s_lshl_b32 s14, s24, 3
	global_load_dwordx4 v[44:47], v6, s[10:11]
	s_add_u32 s10, s10, s14
	s_addc_u32 s11, s11, 0
	global_load_dwordx4 v[48:51], v6, s[10:11]
	s_add_u32 s10, s10, s14
	s_addc_u32 s11, s11, 0
	global_load_dwordx4 v[52:55], v6, s[10:11]
	s_add_u32 s10, s10, s14
	s_addc_u32 s11, s11, 0
	global_load_dwordx4 v[56:59], v6, s[10:11]
	s_add_u32 s10, s10, s14
	s_addc_u32 s11, s11, 0
	global_load_dwordx4 v[60:63], v6, s[10:11]
	s_add_u32 s10, s10, s14
	s_addc_u32 s11, s11, 0
	global_load_dwordx4 v[64:67], v6, s[10:11]
	s_add_u32 s10, s10, s14
	s_addc_u32 s11, s11, 0
	global_load_dwordx4 v[68:71], v6, s[10:11]
	s_add_u32 s10, s10, s14
	s_addc_u32 s11, s11, 0
	global_load_dwordx4 v[72:75], v6, s[10:11]
	global_load_dwordx4 v[76:79], v5, s[12:13]
	global_load_dwordx4 v[80:83], v5, s[12:13] offset:16
	s_add_u32 s20, s20, s21
	s_add_u32 s42, s42, 1

.Ltrp3_p7_ng:
	v_cvt_pk_bf16_f32 v12, v12, v13
	v_cvt_pk_bf16_f32 v13, v14, v15
	v_cvt_pk_bf16_f32 v14, v16, v17
	v_cvt_pk_bf16_f32 v15, v18, v19
	v_cvt_pk_bf16_f32 v20, v20, v21
	v_cvt_pk_bf16_f32 v21, v22, v23
	v_cvt_pk_bf16_f32 v22, v24, v25
	v_cvt_pk_bf16_f32 v23, v26, v27
	v_cvt_pk_bf16_f32 v28, v28, v29
	v_cvt_pk_bf16_f32 v29, v30, v31
	v_cvt_pk_bf16_f32 v30, v32, v33
	v_cvt_pk_bf16_f32 v31, v34, v35
	v_cvt_pk_bf16_f32 v36, v36, v37
	v_cvt_pk_bf16_f32 v37, v38, v39
	v_cvt_pk_bf16_f32 v38, v40, v41
	v_cvt_pk_bf16_f32 v39, v42, v43
	global_store_dwordx4 v8, v[12:15], s[78:79]
	global_store_dwordx4 v9, v[20:23], s[78:79]
	global_store_dwordx4 v10, v[28:31], s[78:79]
	global_store_dwordx4 v11, v[36:39], s[78:79]
	s_sub_u32 s42, s42, 1
	s_add_u32 s43, s43, 1
	s_cmp_ge_u32 s20, 0x3460
	s_cbranch_scc1 .Ltrp3_ni_1
	s_mov_b32 s26, s20
	s_cmp_lt_u32 s26, 0x400
	s_cbranch_scc1 .Ltrp3_i8_s0
	s_sub_u32 s26, s26, 0x400
	s_cmp_lt_u32 s26, 0x400
	s_cbranch_scc1 .Ltrp3_i8_s1
	s_sub_u32 s26, s26, 0x400
	s_cmp_lt_u32 s26, 0x800
	s_cbranch_scc1 .Ltrp3_i8_s2
	s_sub_u32 s26, s26, 0x800
	s_cmp_lt_u32 s26, 0x200
	s_cbranch_scc1 .Ltrp3_i8_s3
	s_sub_u32 s26, s26, 0x200
	s_cmp_lt_u32 s26, 0x200
	s_cbranch_scc1 .Ltrp3_i8_s4
	s_sub_u32 s26, s26, 0x200
	s_cmp_lt_u32 s26, 0x2c00
	s_cbranch_scc1 .Ltrp3_i8_s5
	s_sub_u32 s26, s26, 0x2c00
	s_branch .Ltrp3_i8_s6

.Ltrp3_i8_s1:
	s_mov_b64 s[22:23], s[64:65]
	s_mov_b32 s24, 0x2000
	s_lshr_b32 s25, s26, 6
	s_and_b32 s27, s26, 63
	s_mov_b32 s28, 0x2200800
	s_mov_b32 s29, 0x1000
	s_mov_b32 s30, 0
	s_mov_b32 s31, 0
	s_branch .Ltrp3_i8_c
.Ltrp3_i8_s2:
	s_mov_b64 s[22:23], s[60:61]
	s_mov_b32 s24, 0x2000
	s_lshr_b32 s25, s26, 6
	s_and_b32 s27, s26, 63
	s_mov_b32 s28, 0x2a00000
	s_mov_b32 s29, 0x1000
	s_mov_b32 s30, 0
	s_mov_b32 s31, 0
	s_branch .Ltrp3_i8_c
.Ltrp3_i8_s3:
	s_mov_b64 s[22:23], s[66:67]
	s_mov_b32 s24, 0x800
	s_lshr_b32 s25, s26, 4
	s_and_b32 s27, s26, 15
	s_mov_b32 s28, 0x3200000
	s_mov_b32 s29, 0x1000
	s_mov_b32 s30, 0x2000
	s_mov_b32 s31, 1
	s_branch .Ltrp3_i8_c

.Ltrp3_i8_s6:
	s_mov_b64 s[22:23], s[58:59]
	s_mov_b32 s24, 0x2000
	s_lshr_b32 s25, s26, 6
	s_and_b32 s27, s26, 63
	s_mov_b32 s28, 0x6600000
	s_mov_b32 s29, 0x2c00
	s_mov_b32 s30, 0
	s_mov_b32 s31, 0
.Ltrp3_i8_c:
	s_lshl_b32 s4, s24, 6
	s_mul_i32 s4, s25, s4
	s_lshl_b32 s5, s27, 7
	s_add_u32 s4, s4, s5
	s_add_u32 s10, s22, s4
	s_addc_u32 s11, s23, 0
	v_mad_u32_u24 v6, v1, s24, v2
	s_lshl_b32 s4, s29, 5
	s_mul_i32 s4, s27, s4
	s_lshl_b32 s5, s25, 7
	s_add_u32 s4, s4, s5
	s_add_u32 s4, s4, s28
	s_add_u32 s78, s72, s4
	s_addc_u32 s79, s73, 0
	s_mov_b32 s80, s29
	s_mov_b32 s81, s31
	s_lshl_b32 s4, s25, 8
	s_add_u32 s4, s4, s30
	s_add_u32 s12, s70, s4
	s_addc_u32 s13, s71, 0
	s_lshl_b32 s14, s24, 3
	global_load_dwordx4 v[84:87], v6, s[10:11]
	s_add_u32 s10, s10, s14
	s_addc_u32 s11, s11, 0
	global_load_dwordx4 v[88:91], v6, s[10:11]
	s_add_u32 s10, s10, s14
	s_addc_u32 s11, s11, 0
	global_load_dwordx4 v[92:95], v6, s[10:11]
	s_add_u32 s10, s10, s14
	s_addc_u32 s11, s11, 0
	global_load_dwordx4 v[96:99], v6, s[10:11]
	s_add_u32 s10, s10, s14
	s_addc_u32 s11, s11, 0
	global_load_dwordx4 v[100:103], v6, s[10:11]
	s_add_u32 s10, s10, s14
	s_addc_u32 s11, s11, 0
	global_load_dwordx4 v[104:107], v6, s[10:11]
	s_add_u32 s10, s10, s14
	s_addc_u32 s11, s11, 0
	global_load_dwordx4 v[108:111], v6, s[10:11]
	s_add_u32 s10, s10, s14
	s_addc_u32 s11, s11, 0
	global_load_dwordx4 v[112:115], v6, s[10:11]
	global_load_dwordx4 v[116:119], v5, s[12:13]
	global_load_dwordx4 v[120:123], v5, s[12:13] offset:16
	s_add_u32 s20, s20, s21
	s_add_u32 s42, s42, 1

.Ltrp3_p9_ng:
	v_cvt_pk_bf16_f32 v12, v12, v13
	v_cvt_pk_bf16_f32 v13, v14, v15
	v_cvt_pk_bf16_f32 v14, v16, v17
	v_cvt_pk_bf16_f32 v15, v18, v19
	v_cvt_pk_bf16_f32 v20, v20, v21
	v_cvt_pk_bf16_f32 v21, v22, v23
	v_cvt_pk_bf16_f32 v22, v24, v25
	v_cvt_pk_bf16_f32 v23, v26, v27
	v_cvt_pk_bf16_f32 v28, v28, v29
	v_cvt_pk_bf16_f32 v29, v30, v31
	v_cvt_pk_bf16_f32 v30, v32, v33
	v_cvt_pk_bf16_f32 v31, v34, v35
	v_cvt_pk_bf16_f32 v36, v36, v37
	v_cvt_pk_bf16_f32 v37, v38, v39
	v_cvt_pk_bf16_f32 v38, v40, v41
	v_cvt_pk_bf16_f32 v39, v42, v43
	global_store_dwordx4 v8, v[12:15], s[82:83]
	global_store_dwordx4 v9, v[20:23], s[82:83]
	global_store_dwordx4 v10, v[28:31], s[82:83]
	global_store_dwordx4 v11, v[36:39], s[82:83]
	s_sub_u32 s42, s42, 1
	s_add_u32 s43, s43, 1
	s_cmp_ge_u32 s20, 0x3460
	s_cbranch_scc1 .Ltrp3_ni_2
	s_mov_b32 s26, s20
	s_cmp_lt_u32 s26, 0x400
	s_cbranch_scc1 .Ltrp3_i10_s0
	s_sub_u32 s26, s26, 0x400
	s_cmp_lt_u32 s26, 0x400
	s_cbranch_scc1 .Ltrp3_i10_s1
	s_sub_u32 s26, s26, 0x400
	s_cmp_lt_u32 s26, 0x800
	s_cbranch_scc1 .Ltrp3_i10_s2
	s_sub_u32 s26, s26, 0x800
	s_cmp_lt_u32 s26, 0x200
	s_cbranch_scc1 .Ltrp3_i10_s3
	s_sub_u32 s26, s26, 0x200
	s_cmp_lt_u32 s26, 0x200
	s_cbranch_scc1 .Ltrp3_i10_s4
	s_sub_u32 s26, s26, 0x200
	s_cmp_lt_u32 s26, 0x2c00
	s_cbranch_scc1 .Ltrp3_i10_s5
	s_sub_u32 s26, s26, 0x2c00
	s_branch .Ltrp3_i10_s6

.Ltrp3_i10_s1:
	s_mov_b64 s[22:23], s[64:65]
	s_mov_b32 s24, 0x2000
	s_lshr_b32 s25, s26, 6
	s_and_b32 s27, s26, 63
	s_mov_b32 s28, 0x2200800
	s_mov_b32 s29, 0x1000
	s_mov_b32 s30, 0
	s_mov_b32 s31, 0
	s_branch .Ltrp3_i10_c
.Ltrp3_i10_s2:
	s_mov_b64 s[22:23], s[60:61]
	s_mov_b32 s24, 0x2000
	s_lshr_b32 s25, s26, 6
	s_and_b32 s27, s26, 63
	s_mov_b32 s28, 0x2a00000
	s_mov_b32 s29, 0x1000
	s_mov_b32 s30, 0
	s_mov_b32 s31, 0
	s_branch .Ltrp3_i10_c
.Ltrp3_i10_s3:
	s_mov_b64 s[22:23], s[66:67]
	s_mov_b32 s24, 0x800
	s_lshr_b32 s25, s26, 4
	s_and_b32 s27, s26, 15
	s_mov_b32 s28, 0x3200000
	s_mov_b32 s29, 0x1000
	s_mov_b32 s30, 0x2000
	s_mov_b32 s31, 1
	s_branch .Ltrp3_i10_c

.Ltrp3_i10_s6:
	s_mov_b64 s[22:23], s[58:59]
	s_mov_b32 s24, 0x2000
	s_lshr_b32 s25, s26, 6
	s_and_b32 s27, s26, 63
	s_mov_b32 s28, 0x6600000
	s_mov_b32 s29, 0x2c00
	s_mov_b32 s30, 0
	s_mov_b32 s31, 0
.Ltrp3_i10_c:
	s_lshl_b32 s4, s24, 6
	s_mul_i32 s4, s25, s4
	s_lshl_b32 s5, s27, 7
	s_add_u32 s4, s4, s5
	s_add_u32 s10, s22, s4
	s_addc_u32 s11, s23, 0
	v_mad_u32_u24 v6, v1, s24, v2
	s_lshl_b32 s4, s29, 5
	s_mul_i32 s4, s27, s4
	s_lshl_b32 s5, s25, 7
	s_add_u32 s4, s4, s5
	s_add_u32 s4, s4, s28
	s_add_u32 s82, s72, s4
	s_addc_u32 s83, s73, 0
	s_mov_b32 s84, s29
	s_mov_b32 s85, s31
	s_lshl_b32 s4, s25, 8
	s_add_u32 s4, s4, s30
	s_add_u32 s12, s70, s4
	s_addc_u32 s13, s71, 0
	s_lshl_b32 s14, s24, 3
	global_load_dwordx4 v[124:127], v6, s[10:11]
	s_add_u32 s10, s10, s14
	s_addc_u32 s11, s11, 0
	global_load_dwordx4 v[128:131], v6, s[10:11]
	s_add_u32 s10, s10, s14
	s_addc_u32 s11, s11, 0
	global_load_dwordx4 v[132:135], v6, s[10:11]
	s_add_u32 s10, s10, s14
	s_addc_u32 s11, s11, 0
	global_load_dwordx4 v[136:139], v6, s[10:11]
	s_add_u32 s10, s10, s14
	s_addc_u32 s11, s11, 0
	global_load_dwordx4 v[140:143], v6, s[10:11]
	s_add_u32 s10, s10, s14
	s_addc_u32 s11, s11, 0
	global_load_dwordx4 v[144:147], v6, s[10:11]
	s_add_u32 s10, s10, s14
	s_addc_u32 s11, s11, 0
	global_load_dwordx4 v[148:151], v6, s[10:11]
	s_add_u32 s10, s10, s14
	s_addc_u32 s11, s11, 0
	global_load_dwordx4 v[152:155], v6, s[10:11]
	global_load_dwordx4 v[156:159], v5, s[12:13]
	global_load_dwordx4 v[160:163], v5, s[12:13] offset:16
	s_add_u32 s20, s20, s21
	s_add_u32 s42, s42, 1

.Ltrp3_p11_ng:
	v_cvt_pk_bf16_f32 v12, v12, v13
	v_cvt_pk_bf16_f32 v13, v14, v15
	v_cvt_pk_bf16_f32 v14, v16, v17
	v_cvt_pk_bf16_f32 v15, v18, v19
	v_cvt_pk_bf16_f32 v20, v20, v21
	v_cvt_pk_bf16_f32 v21, v22, v23
	v_cvt_pk_bf16_f32 v22, v24, v25
	v_cvt_pk_bf16_f32 v23, v26, v27
	v_cvt_pk_bf16_f32 v28, v28, v29
	v_cvt_pk_bf16_f32 v29, v30, v31
	v_cvt_pk_bf16_f32 v30, v32, v33
	v_cvt_pk_bf16_f32 v31, v34, v35
	v_cvt_pk_bf16_f32 v36, v36, v37
	v_cvt_pk_bf16_f32 v37, v38, v39
	v_cvt_pk_bf16_f32 v38, v40, v41
	v_cvt_pk_bf16_f32 v39, v42, v43
	global_store_dwordx4 v8, v[12:15], s[86:87]
	global_store_dwordx4 v9, v[20:23], s[86:87]
	global_store_dwordx4 v10, v[28:31], s[86:87]
	global_store_dwordx4 v11, v[36:39], s[86:87]
	s_sub_u32 s42, s42, 1
	s_add_u32 s43, s43, 1
	s_cmp_ge_u32 s20, 0x3460
	s_cbranch_scc1 .Ltrp3_ni_3
	s_mov_b32 s26, s20
	s_cmp_lt_u32 s26, 0x400
	s_cbranch_scc1 .Ltrp3_i12_s0
	s_sub_u32 s26, s26, 0x400
	s_cmp_lt_u32 s26, 0x400
	s_cbranch_scc1 .Ltrp3_i12_s1
	s_sub_u32 s26, s26, 0x400
	s_cmp_lt_u32 s26, 0x800
	s_cbranch_scc1 .Ltrp3_i12_s2
	s_sub_u32 s26, s26, 0x800
	s_cmp_lt_u32 s26, 0x200
	s_cbranch_scc1 .Ltrp3_i12_s3
	s_sub_u32 s26, s26, 0x200
	s_cmp_lt_u32 s26, 0x200
	s_cbranch_scc1 .Ltrp3_i12_s4
	s_sub_u32 s26, s26, 0x200
	s_cmp_lt_u32 s26, 0x2c00
	s_cbranch_scc1 .Ltrp3_i12_s5
	s_sub_u32 s26, s26, 0x2c00
	s_branch .Ltrp3_i12_s6

.Ltrp3_i12_s1:
	s_mov_b64 s[22:23], s[64:65]
	s_mov_b32 s24, 0x2000
	s_lshr_b32 s25, s26, 6
	s_and_b32 s27, s26, 63
	s_mov_b32 s28, 0x2200800
	s_mov_b32 s29, 0x1000
	s_mov_b32 s30, 0
	s_mov_b32 s31, 0
	s_branch .Ltrp3_i12_c
.Ltrp3_i12_s2:
	s_mov_b64 s[22:23], s[60:61]
	s_mov_b32 s24, 0x2000
	s_lshr_b32 s25, s26, 6
	s_and_b32 s27, s26, 63
	s_mov_b32 s28, 0x2a00000
	s_mov_b32 s29, 0x1000
	s_mov_b32 s30, 0
	s_mov_b32 s31, 0
	s_branch .Ltrp3_i12_c
.Ltrp3_i12_s3:
	s_mov_b64 s[22:23], s[66:67]
	s_mov_b32 s24, 0x800
	s_lshr_b32 s25, s26, 4
	s_and_b32 s27, s26, 15
	s_mov_b32 s28, 0x3200000
	s_mov_b32 s29, 0x1000
	s_mov_b32 s30, 0x2000
	s_mov_b32 s31, 1
	s_branch .Ltrp3_i12_c

.Ltrp3_i12_s6:
	s_mov_b64 s[22:23], s[58:59]
	s_mov_b32 s24, 0x2000
	s_lshr_b32 s25, s26, 6
	s_and_b32 s27, s26, 63
	s_mov_b32 s28, 0x6600000
	s_mov_b32 s29, 0x2c00
	s_mov_b32 s30, 0
	s_mov_b32 s31, 0
.Ltrp3_i12_c:
	s_lshl_b32 s4, s24, 6
	s_mul_i32 s4, s25, s4
	s_lshl_b32 s5, s27, 7
	s_add_u32 s4, s4, s5
	s_add_u32 s10, s22, s4
	s_addc_u32 s11, s23, 0
	v_mad_u32_u24 v6, v1, s24, v2
	s_lshl_b32 s4, s29, 5
	s_mul_i32 s4, s27, s4
	s_lshl_b32 s5, s25, 7
	s_add_u32 s4, s4, s5
	s_add_u32 s4, s4, s28
	s_add_u32 s86, s72, s4
	s_addc_u32 s87, s73, 0
	s_mov_b32 s88, s29
	s_mov_b32 s90, s31
	s_lshl_b32 s4, s25, 8
	s_add_u32 s4, s4, s30
	s_add_u32 s12, s70, s4
	s_addc_u32 s13, s71, 0
	s_lshl_b32 s14, s24, 3
	global_load_dwordx4 v[164:167], v6, s[10:11]
	s_add_u32 s10, s10, s14
	s_addc_u32 s11, s11, 0
	global_load_dwordx4 v[168:171], v6, s[10:11]
	s_add_u32 s10, s10, s14
	s_addc_u32 s11, s11, 0
	global_load_dwordx4 v[172:175], v6, s[10:11]
	s_add_u32 s10, s10, s14
	s_addc_u32 s11, s11, 0
	global_load_dwordx4 v[176:179], v6, s[10:11]
	s_add_u32 s10, s10, s14
	s_addc_u32 s11, s11, 0
	global_load_dwordx4 v[180:183], v6, s[10:11]
	s_add_u32 s10, s10, s14
	s_addc_u32 s11, s11, 0
	global_load_dwordx4 v[184:187], v6, s[10:11]
	s_add_u32 s10, s10, s14
	s_addc_u32 s11, s11, 0
	global_load_dwordx4 v[188:191], v6, s[10:11]
	s_add_u32 s10, s10, s14
	s_addc_u32 s11, s11, 0
	global_load_dwordx4 v[192:195], v6, s[10:11]
	global_load_dwordx4 v[196:199], v5, s[12:13]
	global_load_dwordx4 v[200:203], v5, s[12:13] offset:16
	s_add_u32 s20, s20, s21
	s_add_u32 s42, s42, 1

.LBB0_2305:
	s_cmp_eq_u64 s[4:5], 0
	s_cbranch_scc1 .Ltrs10_x
	s_cmp_lt_u32 s2, 132
	s_cbranch_scc1 .Ltrs10_x
	s_mov_b64 exec, -1
	v_readlane_b32 s0, v254, 0
	v_readlane_b32 s1, v254, 1
	s_nop 4
	s_load_dwordx2 s[42:43], s[0:1], 0xa8
	s_load_dwordx2 s[44:45], s[0:1], 0xc0
	s_load_dwordx2 s[46:47], s[0:1], 0x88
	s_load_dwordx2 s[48:49], s[0:1], 0x78
	s_load_dwordx2 s[50:51], s[0:1], 0x80
	s_load_dwordx2 s[52:53], s[0:1], 0x90
	s_load_dwordx2 s[54:55], s[0:1], 0xa0
	s_load_dwordx2 s[56:57], s[0:1], 0x48
	s_load_dwordx2 s[58:59], s[0:1], 0xd8
	s_load_dword s3, s[0:1], 0xe8
	v_readfirstlane_b32 s8, v0
	v_and_b32_e32 v7, 63, v0
	s_lshr_b32 s8, s8, 6
	v_lshrrev_b32_e32 v1, 3, v7
	v_and_b32_e32 v2, 7, v7
	s_lshl_b32 s9, s8, 14
	v_lshlrev_b32_e32 v5, 5, v2
	s_movk_i32 s14, 0x420
	v_mul_u32_u24_e32 v4, s14, v2
	v_lshlrev_b32_e32 v2, 4, v2
	s_movk_i32 s14, 0x84
	v_mad_u32_u24 v3, v1, s14, v2
	v_lshl_add_u32 v4, v1, 2, v4
	v_add_u32_e32 v3, s9, v3
	v_add_u32_e32 v4, s9, v4
	v_mov_b32_e32 v124, v3
	v_add_u32_e32 v125, 1056, v3
	v_add_u32_e32 v126, 2112, v3
	v_add_u32_e32 v127, 3168, v3
	v_add_u32_e32 v128, 4224, v3
	v_add_u32_e32 v129, 5280, v3
	v_add_u32_e32 v130, 6336, v3
	v_add_u32_e32 v131, 7392, v3
	s_waitcnt lgkmcnt(0)
	s_sub_u32 s9, s2, 132
	s_lshl_b32 s9, s9, 3
	s_add_u32 s20, s9, s8
	s_sub_u32 s21, s3, 132
	s_lshl_b32 s21, s21, 3
	s_add_u32 s20, s20, 0x3460
	s_cmp_ge_u32 s20, 0x4000
	s_cbranch_scc1 .Ltrs10_r
	s_mov_b32 s26, s20
	s_cmp_lt_u32 s26, 0x400
	s_cbranch_scc1 .Ltrp10_i1_s0
	s_sub_u32 s26, s26, 0x400
	s_cmp_lt_u32 s26, 0x400
	s_cbranch_scc1 .Ltrp10_i1_s1
	s_sub_u32 s26, s26, 0x400
	s_cmp_lt_u32 s26, 0x800
	s_cbranch_scc1 .Ltrp10_i1_s2
	s_sub_u32 s26, s26, 0x800
	s_cmp_lt_u32 s26, 0x200
	s_cbranch_scc1 .Ltrp10_i1_s3
	s_sub_u32 s26, s26, 0x200
	s_cmp_lt_u32 s26, 0x200
	s_cbranch_scc1 .Ltrp10_i1_s4
	s_sub_u32 s26, s26, 0x200
	s_cmp_lt_u32 s26, 0x2c00
	s_cbranch_scc1 .Ltrp10_i1_s5
	s_sub_u32 s26, s26, 0x2c00
	s_branch .Ltrp10_i1_s6
.Ltrp10_i1_s0:
	s_mov_b64 s[22:23], s[48:49]
	s_mov_b32 s24, 0x2000
	s_lshr_b32 s25, s26, 6
	s_and_b32 s27, s26, 63
	s_mov_b32 s28, 0x2200000
	s_mov_b32 s29, 0x1000
	s_mov_b32 s30, 0
	s_mov_b32 s31, 0
	s_branch .Ltrp10_i1_c
.Ltrp10_i1_s1:
	s_mov_b64 s[22:23], s[50:51]
	s_mov_b32 s24, 0x2000
	s_lshr_b32 s25, s26, 6
	s_and_b32 s27, s26, 63
	s_mov_b32 s28, 0x2200800
	s_mov_b32 s29, 0x1000
	s_mov_b32 s30, 0
	s_mov_b32 s31, 0
	s_branch .Ltrp10_i1_c
.Ltrp10_i1_s2:
	s_mov_b64 s[22:23], s[46:47]
	s_mov_b32 s24, 0x2000
	s_lshr_b32 s25, s26, 6
	s_and_b32 s27, s26, 63
	s_mov_b32 s28, 0x2a00000
	s_mov_b32 s29, 0x1000
	s_mov_b32 s30, 0
	s_mov_b32 s31, 0
	s_branch .Ltrp10_i1_c
.Ltrp10_i1_s3:
	s_mov_b64 s[22:23], s[52:53]
	s_mov_b32 s24, 0x800
	s_lshr_b32 s25, s26, 4
	s_and_b32 s27, s26, 15
	s_mov_b32 s28, 0x3200000
	s_mov_b32 s29, 0x1000
	s_mov_b32 s30, 0x2000
	s_mov_b32 s31, 1
	s_branch .Ltrp10_i1_c
.Ltrp10_i1_s4:
	s_mov_b64 s[22:23], s[54:55]
	s_mov_b32 s24, 0x2000
	s_lshr_b32 s25, s26, 6
	s_and_b32 s27, s26, 63
	s_mov_b32 s28, 0x3800000
	s_mov_b32 s29, 0x400
	s_mov_b32 s30, 0
	s_mov_b32 s31, 0
	s_branch .Ltrp10_i1_c
.Ltrp10_i1_s5:
	s_mov_b64 s[22:23], s[42:43]
	s_mov_b32 s24, 0xb000
	s_mul_hi_u32 s25, s26, 0xba2e8c
	s_mul_i32 s27, s25, 0x160
	s_sub_u32 s27, s26, s27
	s_mov_b32 s28, 0x3a00000
	s_mov_b32 s29, 0x1000
	s_mov_b32 s30, 0x6000
	s_mov_b32 s31, 1
	s_branch .Ltrp10_i1_c
.Ltrp10_i1_s6:
	s_mov_b64 s[22:23], s[44:45]
	s_mov_b32 s24, 0x2000
	s_lshr_b32 s25, s26, 6
	s_and_b32 s27, s26, 63
	s_mov_b32 s28, 0x6600000
	s_mov_b32 s29, 0x2c00
	s_mov_b32 s30, 0
	s_mov_b32 s31, 0
.Ltrp10_i1_c:
	s_lshl_b32 s8, s24, 6
	s_mul_i32 s8, s25, s8
	s_lshl_b32 s9, s27, 7
	s_add_u32 s8, s8, s9
	s_add_u32 s10, s22, s8
	s_addc_u32 s11, s23, 0
	v_mad_u32_u24 v6, v1, s24, v2
	s_lshl_b32 s8, s29, 5
	s_mul_i32 s8, s27, s8
	s_lshl_b32 s9, s25, 7
	s_add_u32 s8, s8, s9
	s_add_u32 s8, s8, s28
	s_add_u32 s34, s58, s8
	s_addc_u32 s35, s59, 0
	s_mov_b32 s36, s29
	s_mov_b32 s37, s31
	s_lshl_b32 s8, s25, 8
	s_add_u32 s8, s8, s30
	s_add_u32 s12, s56, s8
	s_addc_u32 s13, s57, 0
	s_lshl_b32 s14, s24, 3
	global_load_dwordx4 v[44:47], v6, s[10:11]
	s_add_u32 s10, s10, s14
	s_addc_u32 s11, s11, 0
	global_load_dwordx4 v[48:51], v6, s[10:11]
	s_add_u32 s10, s10, s14
	s_addc_u32 s11, s11, 0
	global_load_dwordx4 v[52:55], v6, s[10:11]
	s_add_u32 s10, s10, s14
	s_addc_u32 s11, s11, 0
	global_load_dwordx4 v[56:59], v6, s[10:11]
	s_add_u32 s10, s10, s14
	s_addc_u32 s11, s11, 0
	global_load_dwordx4 v[60:63], v6, s[10:11]
	s_add_u32 s10, s10, s14
	s_addc_u32 s11, s11, 0
	global_load_dwordx4 v[64:67], v6, s[10:11]
	s_add_u32 s10, s10, s14
	s_addc_u32 s11, s11, 0
	global_load_dwordx4 v[68:71], v6, s[10:11]
	s_add_u32 s10, s10, s14
	s_addc_u32 s11, s11, 0
	global_load_dwordx4 v[72:75], v6, s[10:11]
	global_load_dwordx4 v[76:79], v5, s[12:13]
	global_load_dwordx4 v[80:83], v5, s[12:13] offset:16
	s_add_u32 s20, s20, s21
	s_cmp_ge_u32 s20, 0x4000
	s_mov_b32 s16, 0
	s_cbranch_scc1 .Ltrp10_pro_nob
	s_mov_b32 s26, s20
	s_cmp_lt_u32 s26, 0x400
	s_cbranch_scc1 .Ltrp10_i2_s0
	s_sub_u32 s26, s26, 0x400
	s_cmp_lt_u32 s26, 0x400
	s_cbranch_scc1 .Ltrp10_i2_s1
	s_sub_u32 s26, s26, 0x400
	s_cmp_lt_u32 s26, 0x800
	s_cbranch_scc1 .Ltrp10_i2_s2
	s_sub_u32 s26, s26, 0x800
	s_cmp_lt_u32 s26, 0x200
	s_cbranch_scc1 .Ltrp10_i2_s3
	s_sub_u32 s26, s26, 0x200
	s_cmp_lt_u32 s26, 0x200
	s_cbranch_scc1 .Ltrp10_i2_s4
	s_sub_u32 s26, s26, 0x200
	s_cmp_lt_u32 s26, 0x2c00
	s_cbranch_scc1 .Ltrp10_i2_s5
	s_sub_u32 s26, s26, 0x2c00
	s_branch .Ltrp10_i2_s6

.Ltrp10_i2_c:
	s_lshl_b32 s8, s24, 6
	s_mul_i32 s8, s25, s8
	s_lshl_b32 s9, s27, 7
	s_add_u32 s8, s8, s9
	s_add_u32 s10, s22, s8
	s_addc_u32 s11, s23, 0
	v_mad_u32_u24 v6, v1, s24, v2
	s_lshl_b32 s8, s29, 5
	s_mul_i32 s8, s27, s8
	s_lshl_b32 s9, s25, 7
	s_add_u32 s8, s8, s9
	s_add_u32 s8, s8, s28
	s_add_u32 s38, s58, s8
	s_addc_u32 s39, s59, 0
	s_mov_b32 s40, s29
	s_mov_b32 s41, s31
	s_lshl_b32 s8, s25, 8
	s_add_u32 s8, s8, s30
	s_add_u32 s12, s56, s8
	s_addc_u32 s13, s57, 0
	s_lshl_b32 s14, s24, 3
	global_load_dwordx4 v[84:87], v6, s[10:11]
	s_add_u32 s10, s10, s14
	s_addc_u32 s11, s11, 0
	global_load_dwordx4 v[88:91], v6, s[10:11]
	s_add_u32 s10, s10, s14
	s_addc_u32 s11, s11, 0
	global_load_dwordx4 v[92:95], v6, s[10:11]
	s_add_u32 s10, s10, s14
	s_addc_u32 s11, s11, 0
	global_load_dwordx4 v[96:99], v6, s[10:11]
	s_add_u32 s10, s10, s14
	s_addc_u32 s11, s11, 0
	global_load_dwordx4 v[100:103], v6, s[10:11]
	s_add_u32 s10, s10, s14
	s_addc_u32 s11, s11, 0
	global_load_dwordx4 v[104:107], v6, s[10:11]
	s_add_u32 s10, s10, s14
	s_addc_u32 s11, s11, 0
	global_load_dwordx4 v[108:111], v6, s[10:11]
	s_add_u32 s10, s10, s14
	s_addc_u32 s11, s11, 0
	global_load_dwordx4 v[112:115], v6, s[10:11]
	global_load_dwordx4 v[116:119], v5, s[12:13]
	global_load_dwordx4 v[120:123], v5, s[12:13] offset:16
	s_add_u32 s20, s20, s21
	s_mov_b32 s16, 1
	s_waitcnt vmcnt(10)
	s_branch .Ltrp10_loopA

.Ltrp10_loopA:
	ds_write2_b32 v124, v44, v45 offset1:1
	ds_write2_b32 v124, v46, v47 offset0:2 offset1:3
	ds_write2_b32 v125, v48, v49 offset1:1
	ds_write2_b32 v125, v50, v51 offset0:2 offset1:3
	ds_write2_b32 v126, v52, v53 offset1:1
	ds_write2_b32 v126, v54, v55 offset0:2 offset1:3
	ds_write2_b32 v127, v56, v57 offset1:1
	ds_write2_b32 v127, v58, v59 offset0:2 offset1:3
	ds_write2_b32 v128, v60, v61 offset1:1
	ds_write2_b32 v128, v62, v63 offset0:2 offset1:3
	ds_write2_b32 v129, v64, v65 offset1:1
	ds_write2_b32 v129, v66, v67 offset0:2 offset1:3
	ds_write2_b32 v130, v68, v69 offset1:1
	ds_write2_b32 v130, v70, v71 offset0:2 offset1:3
	ds_write2_b32 v131, v72, v73 offset1:1
	ds_write2_b32 v131, v74, v75 offset0:2 offset1:3
	v_mad_u32_u24 v8, v1, s36, v2
	s_lshl_b32 s8, s36, 3
	s_nop 0
	v_add_u32_e32 v9, s8, v8
	v_add_u32_e32 v10, s8, v9
	v_add_u32_e32 v11, s8, v10
	s_waitcnt lgkmcnt(0)
	ds_read2_b32 v[12:13], v4 offset1:33
	ds_read2_b32 v[14:15], v4 offset0:66 offset1:99
	ds_read2_b32 v[16:17], v4 offset0:132 offset1:165
	ds_read2_b32 v[18:19], v4 offset0:198 offset1:231
	ds_read2_b32 v[20:21], v4 offset0:8 offset1:41
	ds_read2_b32 v[22:23], v4 offset0:74 offset1:107
	ds_read2_b32 v[24:25], v4 offset0:140 offset1:173
	ds_read2_b32 v[26:27], v4 offset0:206 offset1:239
	ds_read2_b32 v[28:29], v4 offset0:16 offset1:49
	ds_read2_b32 v[30:31], v4 offset0:82 offset1:115
	ds_read2_b32 v[32:33], v4 offset0:148 offset1:181
	ds_read2_b32 v[34:35], v4 offset0:214 offset1:247
	ds_read2_b32 v[36:37], v4 offset0:24 offset1:57
	ds_read2_b32 v[38:39], v4 offset0:90 offset1:123
	ds_read2_b32 v[40:41], v4 offset0:156 offset1:189
	ds_read2_b32 v[42:43], v4 offset0:222 offset1:255
	s_cmp_eq_u32 s37, 0
	s_waitcnt lgkmcnt(0)
	s_cbranch_scc1 .Ltrp10_p3_ng
	v_mul_f32_e32 v12, v76, v12
	v_mul_f32_e32 v13, v77, v13
	v_mul_f32_e32 v14, v78, v14
	v_mul_f32_e32 v15, v79, v15
	v_mul_f32_e32 v16, v80, v16
	v_mul_f32_e32 v17, v81, v17
	v_mul_f32_e32 v18, v82, v18
	v_mul_f32_e32 v19, v83, v19
	v_mul_f32_e32 v20, v76, v20
	v_mul_f32_e32 v21, v77, v21
	v_mul_f32_e32 v22, v78, v22
	v_mul_f32_e32 v23, v79, v23
	v_mul_f32_e32 v24, v80, v24
	v_mul_f32_e32 v25, v81, v25
	v_mul_f32_e32 v26, v82, v26
	v_mul_f32_e32 v27, v83, v27
	v_mul_f32_e32 v28, v76, v28
	v_mul_f32_e32 v29, v77, v29
	v_mul_f32_e32 v30, v78, v30
	v_mul_f32_e32 v31, v79, v31
	v_mul_f32_e32 v32, v80, v32
	v_mul_f32_e32 v33, v81, v33
	v_mul_f32_e32 v34, v82, v34
	v_mul_f32_e32 v35, v83, v35
	v_mul_f32_e32 v36, v76, v36
	v_mul_f32_e32 v37, v77, v37
	v_mul_f32_e32 v38, v78, v38
	v_mul_f32_e32 v39, v79, v39
	v_mul_f32_e32 v40, v80, v40
	v_mul_f32_e32 v41, v81, v41
	v_mul_f32_e32 v42, v82, v42
	v_mul_f32_e32 v43, v83, v43
.Ltrp10_p3_ng:
	v_cvt_pk_bf16_f32 v12, v12, v13
	v_cvt_pk_bf16_f32 v13, v14, v15
	v_cvt_pk_bf16_f32 v14, v16, v17
	v_cvt_pk_bf16_f32 v15, v18, v19
	v_cvt_pk_bf16_f32 v20, v20, v21
	v_cvt_pk_bf16_f32 v21, v22, v23
	v_cvt_pk_bf16_f32 v22, v24, v25
	v_cvt_pk_bf16_f32 v23, v26, v27
	v_cvt_pk_bf16_f32 v28, v28, v29
	v_cvt_pk_bf16_f32 v29, v30, v31
	v_cvt_pk_bf16_f32 v30, v32, v33
	v_cvt_pk_bf16_f32 v31, v34, v35
	v_cvt_pk_bf16_f32 v36, v36, v37
	v_cvt_pk_bf16_f32 v37, v38, v39
	v_cvt_pk_bf16_f32 v38, v40, v41
	v_cvt_pk_bf16_f32 v39, v42, v43
	global_store_dwordx4 v8, v[12:15], s[34:35]
	global_store_dwordx4 v9, v[20:23], s[34:35]
	global_store_dwordx4 v10, v[28:31], s[34:35]
	global_store_dwordx4 v11, v[36:39], s[34:35]
	s_cmp_ge_u32 s20, 0x4000
	s_mov_b32 s15, 0
	s_cbranch_scc1 .Ltrp10_skipA
	s_mov_b32 s26, s20
	s_cmp_lt_u32 s26, 0x400
	s_cbranch_scc1 .Ltrp10_i4_s0
	s_sub_u32 s26, s26, 0x400
	s_cmp_lt_u32 s26, 0x400
	s_cbranch_scc1 .Ltrp10_i4_s1
	s_sub_u32 s26, s26, 0x400
	s_cmp_lt_u32 s26, 0x800
	s_cbranch_scc1 .Ltrp10_i4_s2
	s_sub_u32 s26, s26, 0x800
	s_cmp_lt_u32 s26, 0x200
	s_cbranch_scc1 .Ltrp10_i4_s3
	s_sub_u32 s26, s26, 0x200
	s_cmp_lt_u32 s26, 0x200
	s_cbranch_scc1 .Ltrp10_i4_s4
	s_sub_u32 s26, s26, 0x200
	s_cmp_lt_u32 s26, 0x2c00
	s_cbranch_scc1 .Ltrp10_i4_s5
	s_sub_u32 s26, s26, 0x2c00
	s_branch .Ltrp10_i4_s6

.Ltrp10_i4_c:
	s_lshl_b32 s8, s24, 6
	s_mul_i32 s8, s25, s8
	s_lshl_b32 s9, s27, 7
	s_add_u32 s8, s8, s9
	s_add_u32 s10, s22, s8
	s_addc_u32 s11, s23, 0
	v_mad_u32_u24 v6, v1, s24, v2
	s_lshl_b32 s8, s29, 5
	s_mul_i32 s8, s27, s8
	s_lshl_b32 s9, s25, 7
	s_add_u32 s8, s8, s9
	s_add_u32 s8, s8, s28
	s_add_u32 s34, s58, s8
	s_addc_u32 s35, s59, 0
	s_mov_b32 s36, s29
	s_mov_b32 s37, s31
	s_lshl_b32 s8, s25, 8
	s_add_u32 s8, s8, s30
	s_add_u32 s12, s56, s8
	s_addc_u32 s13, s57, 0
	s_lshl_b32 s14, s24, 3
	global_load_dwordx4 v[44:47], v6, s[10:11]
	s_add_u32 s10, s10, s14
	s_addc_u32 s11, s11, 0
	global_load_dwordx4 v[48:51], v6, s[10:11]
	s_add_u32 s10, s10, s14
	s_addc_u32 s11, s11, 0
	global_load_dwordx4 v[52:55], v6, s[10:11]
	s_add_u32 s10, s10, s14
	s_addc_u32 s11, s11, 0
	global_load_dwordx4 v[56:59], v6, s[10:11]
	s_add_u32 s10, s10, s14
	s_addc_u32 s11, s11, 0
	global_load_dwordx4 v[60:63], v6, s[10:11]
	s_add_u32 s10, s10, s14
	s_addc_u32 s11, s11, 0
	global_load_dwordx4 v[64:67], v6, s[10:11]
	s_add_u32 s10, s10, s14
	s_addc_u32 s11, s11, 0
	global_load_dwordx4 v[68:71], v6, s[10:11]
	s_add_u32 s10, s10, s14
	s_addc_u32 s11, s11, 0
	global_load_dwordx4 v[72:75], v6, s[10:11]
	global_load_dwordx4 v[76:79], v5, s[12:13]
	global_load_dwordx4 v[80:83], v5, s[12:13] offset:16
	s_add_u32 s20, s20, s21
	s_mov_b32 s15, 1
.Ltrp10_skipA:
	s_cmp_eq_u32 s16, 0
	s_cbranch_scc1 .Ltrs10_r
	s_cmp_eq_u32 s15, 0
	s_cbranch_scc1 .Ltrp10_wB0
	s_waitcnt vmcnt(14)
	s_branch .Ltrp10_doB

.Ltrp10_doB:
	ds_write2_b32 v124, v84, v85 offset1:1
	ds_write2_b32 v124, v86, v87 offset0:2 offset1:3
	ds_write2_b32 v125, v88, v89 offset1:1
	ds_write2_b32 v125, v90, v91 offset0:2 offset1:3
	ds_write2_b32 v126, v92, v93 offset1:1
	ds_write2_b32 v126, v94, v95 offset0:2 offset1:3
	ds_write2_b32 v127, v96, v97 offset1:1
	ds_write2_b32 v127, v98, v99 offset0:2 offset1:3
	ds_write2_b32 v128, v100, v101 offset1:1
	ds_write2_b32 v128, v102, v103 offset0:2 offset1:3
	ds_write2_b32 v129, v104, v105 offset1:1
	ds_write2_b32 v129, v106, v107 offset0:2 offset1:3
	ds_write2_b32 v130, v108, v109 offset1:1
	ds_write2_b32 v130, v110, v111 offset0:2 offset1:3
	ds_write2_b32 v131, v112, v113 offset1:1
	ds_write2_b32 v131, v114, v115 offset0:2 offset1:3
	v_mad_u32_u24 v8, v1, s40, v2
	s_lshl_b32 s8, s40, 3
	s_nop 0
	v_add_u32_e32 v9, s8, v8
	v_add_u32_e32 v10, s8, v9
	v_add_u32_e32 v11, s8, v10
	s_waitcnt lgkmcnt(0)
	ds_read2_b32 v[12:13], v4 offset1:33
	ds_read2_b32 v[14:15], v4 offset0:66 offset1:99
	ds_read2_b32 v[16:17], v4 offset0:132 offset1:165
	ds_read2_b32 v[18:19], v4 offset0:198 offset1:231
	ds_read2_b32 v[20:21], v4 offset0:8 offset1:41
	ds_read2_b32 v[22:23], v4 offset0:74 offset1:107
	ds_read2_b32 v[24:25], v4 offset0:140 offset1:173
	ds_read2_b32 v[26:27], v4 offset0:206 offset1:239
	ds_read2_b32 v[28:29], v4 offset0:16 offset1:49
	ds_read2_b32 v[30:31], v4 offset0:82 offset1:115
	ds_read2_b32 v[32:33], v4 offset0:148 offset1:181
	ds_read2_b32 v[34:35], v4 offset0:214 offset1:247
	ds_read2_b32 v[36:37], v4 offset0:24 offset1:57
	ds_read2_b32 v[38:39], v4 offset0:90 offset1:123
	ds_read2_b32 v[40:41], v4 offset0:156 offset1:189
	ds_read2_b32 v[42:43], v4 offset0:222 offset1:255
	s_cmp_eq_u32 s41, 0
	s_waitcnt lgkmcnt(0)
	s_cbranch_scc1 .Ltrp10_p5_ng
	v_mul_f32_e32 v12, v116, v12
	v_mul_f32_e32 v13, v117, v13
	v_mul_f32_e32 v14, v118, v14
	v_mul_f32_e32 v15, v119, v15
	v_mul_f32_e32 v16, v120, v16
	v_mul_f32_e32 v17, v121, v17
	v_mul_f32_e32 v18, v122, v18
	v_mul_f32_e32 v19, v123, v19
	v_mul_f32_e32 v20, v116, v20
	v_mul_f32_e32 v21, v117, v21
	v_mul_f32_e32 v22, v118, v22
	v_mul_f32_e32 v23, v119, v23
	v_mul_f32_e32 v24, v120, v24
	v_mul_f32_e32 v25, v121, v25
	v_mul_f32_e32 v26, v122, v26
	v_mul_f32_e32 v27, v123, v27
	v_mul_f32_e32 v28, v116, v28
	v_mul_f32_e32 v29, v117, v29
	v_mul_f32_e32 v30, v118, v30
	v_mul_f32_e32 v31, v119, v31
	v_mul_f32_e32 v32, v120, v32
	v_mul_f32_e32 v33, v121, v33
	v_mul_f32_e32 v34, v122, v34
	v_mul_f32_e32 v35, v123, v35
	v_mul_f32_e32 v36, v116, v36
	v_mul_f32_e32 v37, v117, v37
	v_mul_f32_e32 v38, v118, v38
	v_mul_f32_e32 v39, v119, v39
	v_mul_f32_e32 v40, v120, v40
	v_mul_f32_e32 v41, v121, v41
	v_mul_f32_e32 v42, v122, v42
	v_mul_f32_e32 v43, v123, v43
.Ltrp10_p5_ng:
	v_cvt_pk_bf16_f32 v12, v12, v13
	v_cvt_pk_bf16_f32 v13, v14, v15
	v_cvt_pk_bf16_f32 v14, v16, v17
	v_cvt_pk_bf16_f32 v15, v18, v19
	v_cvt_pk_bf16_f32 v20, v20, v21
	v_cvt_pk_bf16_f32 v21, v22, v23
	v_cvt_pk_bf16_f32 v22, v24, v25
	v_cvt_pk_bf16_f32 v23, v26, v27
	v_cvt_pk_bf16_f32 v28, v28, v29
	v_cvt_pk_bf16_f32 v29, v30, v31
	v_cvt_pk_bf16_f32 v30, v32, v33
	v_cvt_pk_bf16_f32 v31, v34, v35
	v_cvt_pk_bf16_f32 v36, v36, v37
	v_cvt_pk_bf16_f32 v37, v38, v39
	v_cvt_pk_bf16_f32 v38, v40, v41
	v_cvt_pk_bf16_f32 v39, v42, v43
	global_store_dwordx4 v8, v[12:15], s[38:39]
	global_store_dwordx4 v9, v[20:23], s[38:39]
	global_store_dwordx4 v10, v[28:31], s[38:39]
	global_store_dwordx4 v11, v[36:39], s[38:39]
	s_cmp_ge_u32 s20, 0x4000
	s_mov_b32 s16, 0
	s_cbranch_scc1 .Ltrp10_skipB
	s_mov_b32 s26, s20
	s_cmp_lt_u32 s26, 0x400
	s_cbranch_scc1 .Ltrp10_i6_s0
	s_sub_u32 s26, s26, 0x400
	s_cmp_lt_u32 s26, 0x400
	s_cbranch_scc1 .Ltrp10_i6_s1
	s_sub_u32 s26, s26, 0x400
	s_cmp_lt_u32 s26, 0x800
	s_cbranch_scc1 .Ltrp10_i6_s2
	s_sub_u32 s26, s26, 0x800
	s_cmp_lt_u32 s26, 0x200
	s_cbranch_scc1 .Ltrp10_i6_s3
	s_sub_u32 s26, s26, 0x200
	s_cmp_lt_u32 s26, 0x200
	s_cbranch_scc1 .Ltrp10_i6_s4
	s_sub_u32 s26, s26, 0x200
	s_cmp_lt_u32 s26, 0x2c00
	s_cbranch_scc1 .Ltrp10_i6_s5
	s_sub_u32 s26, s26, 0x2c00
	s_branch .Ltrp10_i6_s6

.Ltrp10_i6_c:
	s_lshl_b32 s8, s24, 6
	s_mul_i32 s8, s25, s8
	s_lshl_b32 s9, s27, 7
	s_add_u32 s8, s8, s9
	s_add_u32 s10, s22, s8
	s_addc_u32 s11, s23, 0
	v_mad_u32_u24 v6, v1, s24, v2
	s_lshl_b32 s8, s29, 5
	s_mul_i32 s8, s27, s8
	s_lshl_b32 s9, s25, 7
	s_add_u32 s8, s8, s9
	s_add_u32 s8, s8, s28
	s_add_u32 s38, s58, s8
	s_addc_u32 s39, s59, 0
	s_mov_b32 s40, s29
	s_mov_b32 s41, s31
	s_lshl_b32 s8, s25, 8
	s_add_u32 s8, s8, s30
	s_add_u32 s12, s56, s8
	s_addc_u32 s13, s57, 0
	s_lshl_b32 s14, s24, 3
	global_load_dwordx4 v[84:87], v6, s[10:11]
	s_add_u32 s10, s10, s14
	s_addc_u32 s11, s11, 0
	global_load_dwordx4 v[88:91], v6, s[10:11]
	s_add_u32 s10, s10, s14
	s_addc_u32 s11, s11, 0
	global_load_dwordx4 v[92:95], v6, s[10:11]
	s_add_u32 s10, s10, s14
	s_addc_u32 s11, s11, 0
	global_load_dwordx4 v[96:99], v6, s[10:11]
	s_add_u32 s10, s10, s14
	s_addc_u32 s11, s11, 0
	global_load_dwordx4 v[100:103], v6, s[10:11]
	s_add_u32 s10, s10, s14
	s_addc_u32 s11, s11, 0
	global_load_dwordx4 v[104:107], v6, s[10:11]
	s_add_u32 s10, s10, s14
	s_addc_u32 s11, s11, 0
	global_load_dwordx4 v[108:111], v6, s[10:11]
	s_add_u32 s10, s10, s14
	s_addc_u32 s11, s11, 0
	global_load_dwordx4 v[112:115], v6, s[10:11]
	global_load_dwordx4 v[116:119], v5, s[12:13]
	global_load_dwordx4 v[120:123], v5, s[12:13] offset:16
	s_add_u32 s20, s20, s21
	s_mov_b32 s16, 1
.Ltrp10_skipB:
	s_cmp_eq_u32 s15, 0
	s_cbranch_scc1 .Ltrs10_r
	s_cmp_eq_u32 s16, 0
	s_cbranch_scc1 .Ltrp10_wA0
	s_waitcnt vmcnt(14)
	s_branch .Ltrp10_loopA

.Ltrs10_r:
	v_readlane_b32 s48, v254, 40
	v_readlane_b32 s49, v254, 41
	v_readlane_b32 s50, v254, 42
	v_readlane_b32 s51, v254, 43
	v_readlane_b32 s52, v254, 44
	v_readlane_b32 s53, v254, 45
	v_readlane_b32 s54, v254, 46
	v_readlane_b32 s55, v254, 47
	s_nop 4

.LBB0_2709:
	s_cmp_eq_u64 s[6:7], 0
	s_cbranch_scc1 .Ltrs14_x
	s_cmpk_lt_u32 s2, 172
	s_cbranch_scc1 .Ltrs14_x
	s_mov_b64 exec, -1
	v_readlane_b32 s0, v254, 0
	v_readlane_b32 s1, v254, 1
	s_nop 4
	s_load_dwordx2 s[42:43], s[0:1], 0xa8
	s_load_dwordx2 s[44:45], s[0:1], 0xc0
	s_load_dwordx2 s[46:47], s[0:1], 0x88
	s_load_dwordx2 s[48:49], s[0:1], 0x78
	s_load_dwordx2 s[50:51], s[0:1], 0x80
	s_load_dwordx2 s[52:53], s[0:1], 0x90
	s_load_dwordx2 s[54:55], s[0:1], 0xa0
	s_load_dwordx2 s[56:57], s[0:1], 0x48
	s_load_dwordx2 s[58:59], s[0:1], 0xd8
	s_load_dword s3, s[0:1], 0xe8
	v_readfirstlane_b32 s8, v0
	v_and_b32_e32 v7, 63, v0
	s_lshr_b32 s8, s8, 6
	v_lshrrev_b32_e32 v1, 3, v7
	v_and_b32_e32 v2, 7, v7
	s_lshl_b32 s9, s8, 14
	v_lshlrev_b32_e32 v5, 5, v2
	s_movk_i32 s14, 0x420
	v_mul_u32_u24_e32 v4, s14, v2
	v_lshlrev_b32_e32 v2, 4, v2
	s_movk_i32 s14, 0x84
	v_mad_u32_u24 v3, v1, s14, v2
	v_lshl_add_u32 v4, v1, 2, v4
	v_add_u32_e32 v3, s9, v3
	v_add_u32_e32 v4, s9, v4
	v_mov_b32_e32 v124, v3
	v_add_u32_e32 v125, 1056, v3
	v_add_u32_e32 v126, 2112, v3
	v_add_u32_e32 v127, 3168, v3
	v_add_u32_e32 v128, 4224, v3
	v_add_u32_e32 v129, 5280, v3
	v_add_u32_e32 v130, 6336, v3
	v_add_u32_e32 v131, 7392, v3
	s_waitcnt lgkmcnt(0)
	s_sub_u32 s9, s2, 172
	s_lshl_b32 s9, s9, 3
	s_add_u32 s20, s9, s8
	s_sub_u32 s21, s3, 172
	s_lshl_b32 s21, s21, 3
	s_add_u32 s20, s20, 0x4000
	s_cmp_ge_u32 s20, 0x5600
	s_cbranch_scc1 .Ltrs14_r
	s_mov_b32 s26, s20
	s_cmp_lt_u32 s26, 0x400
	s_cbranch_scc1 .Ltrp14_i1_s0
	s_sub_u32 s26, s26, 0x400
	s_cmp_lt_u32 s26, 0x400
	s_cbranch_scc1 .Ltrp14_i1_s1
	s_sub_u32 s26, s26, 0x400
	s_cmp_lt_u32 s26, 0x800
	s_cbranch_scc1 .Ltrp14_i1_s2
	s_sub_u32 s26, s26, 0x800
	s_cmp_lt_u32 s26, 0x200
	s_cbranch_scc1 .Ltrp14_i1_s3
	s_sub_u32 s26, s26, 0x200
	s_cmp_lt_u32 s26, 0x200
	s_cbranch_scc1 .Ltrp14_i1_s4
	s_sub_u32 s26, s26, 0x200
	s_cmp_lt_u32 s26, 0x2c00
	s_cbranch_scc1 .Ltrp14_i1_s5
	s_sub_u32 s26, s26, 0x2c00
	s_branch .Ltrp14_i1_s6

.Ltrp14_i1_c:
	s_lshl_b32 s8, s24, 6
	s_mul_i32 s8, s25, s8
	s_lshl_b32 s9, s27, 7
	s_add_u32 s8, s8, s9
	s_add_u32 s10, s22, s8
	s_addc_u32 s11, s23, 0
	v_mad_u32_u24 v6, v1, s24, v2
	s_lshl_b32 s8, s29, 5
	s_mul_i32 s8, s27, s8
	s_lshl_b32 s9, s25, 7
	s_add_u32 s8, s8, s9
	s_add_u32 s8, s8, s28
	s_add_u32 s34, s58, s8
	s_addc_u32 s35, s59, 0
	s_mov_b32 s36, s29
	s_mov_b32 s37, s31
	s_lshl_b32 s8, s25, 8
	s_add_u32 s8, s8, s30
	s_add_u32 s12, s56, s8
	s_addc_u32 s13, s57, 0
	s_lshl_b32 s14, s24, 3
	global_load_dwordx4 v[44:47], v6, s[10:11]
	s_add_u32 s10, s10, s14
	s_addc_u32 s11, s11, 0
	global_load_dwordx4 v[48:51], v6, s[10:11]
	s_add_u32 s10, s10, s14
	s_addc_u32 s11, s11, 0
	global_load_dwordx4 v[52:55], v6, s[10:11]
	s_add_u32 s10, s10, s14
	s_addc_u32 s11, s11, 0
	global_load_dwordx4 v[56:59], v6, s[10:11]
	s_add_u32 s10, s10, s14
	s_addc_u32 s11, s11, 0
	global_load_dwordx4 v[60:63], v6, s[10:11]
	s_add_u32 s10, s10, s14
	s_addc_u32 s11, s11, 0
	global_load_dwordx4 v[64:67], v6, s[10:11]
	s_add_u32 s10, s10, s14
	s_addc_u32 s11, s11, 0
	global_load_dwordx4 v[68:71], v6, s[10:11]
	s_add_u32 s10, s10, s14
	s_addc_u32 s11, s11, 0
	global_load_dwordx4 v[72:75], v6, s[10:11]
	global_load_dwordx4 v[76:79], v5, s[12:13]
	global_load_dwordx4 v[80:83], v5, s[12:13] offset:16
	s_add_u32 s20, s20, s21
	s_cmp_ge_u32 s20, 0x5600
	s_mov_b32 s16, 0
	s_cbranch_scc1 .Ltrp14_pro_nob
	s_mov_b32 s26, s20
	s_cmp_lt_u32 s26, 0x400
	s_cbranch_scc1 .Ltrp14_i2_s0
	s_sub_u32 s26, s26, 0x400
	s_cmp_lt_u32 s26, 0x400
	s_cbranch_scc1 .Ltrp14_i2_s1
	s_sub_u32 s26, s26, 0x400
	s_cmp_lt_u32 s26, 0x800
	s_cbranch_scc1 .Ltrp14_i2_s2
	s_sub_u32 s26, s26, 0x800
	s_cmp_lt_u32 s26, 0x200
	s_cbranch_scc1 .Ltrp14_i2_s3
	s_sub_u32 s26, s26, 0x200
	s_cmp_lt_u32 s26, 0x200
	s_cbranch_scc1 .Ltrp14_i2_s4
	s_sub_u32 s26, s26, 0x200
	s_cmp_lt_u32 s26, 0x2c00
	s_cbranch_scc1 .Ltrp14_i2_s5
	s_sub_u32 s26, s26, 0x2c00
	s_branch .Ltrp14_i2_s6

.Ltrp14_p3_ng:
	v_cvt_pk_bf16_f32 v12, v12, v13
	v_cvt_pk_bf16_f32 v13, v14, v15
	v_cvt_pk_bf16_f32 v14, v16, v17
	v_cvt_pk_bf16_f32 v15, v18, v19
	v_cvt_pk_bf16_f32 v20, v20, v21
	v_cvt_pk_bf16_f32 v21, v22, v23
	v_cvt_pk_bf16_f32 v22, v24, v25
	v_cvt_pk_bf16_f32 v23, v26, v27
	v_cvt_pk_bf16_f32 v28, v28, v29
	v_cvt_pk_bf16_f32 v29, v30, v31
	v_cvt_pk_bf16_f32 v30, v32, v33
	v_cvt_pk_bf16_f32 v31, v34, v35
	v_cvt_pk_bf16_f32 v36, v36, v37
	v_cvt_pk_bf16_f32 v37, v38, v39
	v_cvt_pk_bf16_f32 v38, v40, v41
	v_cvt_pk_bf16_f32 v39, v42, v43
	global_store_dwordx4 v8, v[12:15], s[34:35]
	global_store_dwordx4 v9, v[20:23], s[34:35]
	global_store_dwordx4 v10, v[28:31], s[34:35]
	global_store_dwordx4 v11, v[36:39], s[34:35]
	s_cmp_ge_u32 s20, 0x5600
	s_mov_b32 s15, 0
	s_cbranch_scc1 .Ltrp14_skipA
	s_mov_b32 s26, s20
	s_cmp_lt_u32 s26, 0x400
	s_cbranch_scc1 .Ltrp14_i4_s0
	s_sub_u32 s26, s26, 0x400
	s_cmp_lt_u32 s26, 0x400
	s_cbranch_scc1 .Ltrp14_i4_s1
	s_sub_u32 s26, s26, 0x400
	s_cmp_lt_u32 s26, 0x800
	s_cbranch_scc1 .Ltrp14_i4_s2
	s_sub_u32 s26, s26, 0x800
	s_cmp_lt_u32 s26, 0x200
	s_cbranch_scc1 .Ltrp14_i4_s3
	s_sub_u32 s26, s26, 0x200
	s_cmp_lt_u32 s26, 0x200
	s_cbranch_scc1 .Ltrp14_i4_s4
	s_sub_u32 s26, s26, 0x200
	s_cmp_lt_u32 s26, 0x2c00
	s_cbranch_scc1 .Ltrp14_i4_s5
	s_sub_u32 s26, s26, 0x2c00
	s_branch .Ltrp14_i4_s6

.Ltrp14_p5_ng:
	v_cvt_pk_bf16_f32 v12, v12, v13
	v_cvt_pk_bf16_f32 v13, v14, v15
	v_cvt_pk_bf16_f32 v14, v16, v17
	v_cvt_pk_bf16_f32 v15, v18, v19
	v_cvt_pk_bf16_f32 v20, v20, v21
	v_cvt_pk_bf16_f32 v21, v22, v23
	v_cvt_pk_bf16_f32 v22, v24, v25
	v_cvt_pk_bf16_f32 v23, v26, v27
	v_cvt_pk_bf16_f32 v28, v28, v29
	v_cvt_pk_bf16_f32 v29, v30, v31
	v_cvt_pk_bf16_f32 v30, v32, v33
	v_cvt_pk_bf16_f32 v31, v34, v35
	v_cvt_pk_bf16_f32 v36, v36, v37
	v_cvt_pk_bf16_f32 v37, v38, v39
	v_cvt_pk_bf16_f32 v38, v40, v41
	v_cvt_pk_bf16_f32 v39, v42, v43
	global_store_dwordx4 v8, v[12:15], s[38:39]
	global_store_dwordx4 v9, v[20:23], s[38:39]
	global_store_dwordx4 v10, v[28:31], s[38:39]
	global_store_dwordx4 v11, v[36:39], s[38:39]
	s_cmp_ge_u32 s20, 0x5600
	s_mov_b32 s16, 0
	s_cbranch_scc1 .Ltrp14_skipB
	s_mov_b32 s26, s20
	s_cmp_lt_u32 s26, 0x400
	s_cbranch_scc1 .Ltrp14_i6_s0
	s_sub_u32 s26, s26, 0x400
	s_cmp_lt_u32 s26, 0x400
	s_cbranch_scc1 .Ltrp14_i6_s1
	s_sub_u32 s26, s26, 0x400
	s_cmp_lt_u32 s26, 0x800
	s_cbranch_scc1 .Ltrp14_i6_s2
	s_sub_u32 s26, s26, 0x800
	s_cmp_lt_u32 s26, 0x200
	s_cbranch_scc1 .Ltrp14_i6_s3
	s_sub_u32 s26, s26, 0x200
	s_cmp_lt_u32 s26, 0x200
	s_cbranch_scc1 .Ltrp14_i6_s4
	s_sub_u32 s26, s26, 0x200
	s_cmp_lt_u32 s26, 0x2c00
	s_cbranch_scc1 .Ltrp14_i6_s5
	s_sub_u32 s26, s26, 0x2c00
	s_branch .Ltrp14_i6_s6
